# ml_seq only: s_setprio 1 for waves 0-3 (critical output-product waves), reset to 0 at next grid barrier
# baseline (speedup 1.0000x reference)
.LBB0_754:
	s_or_b64 exec, exec, s[2:3]
	v_readfirstlane_b32 s32, v178
	s_nop 3
	s_cmp_lt_u32 s32, 0x100
	s_cbranch_scc0 .Lseqprio_skip
	s_setprio 1
.Lseqprio_skip:
	s_mov_b64 s[2:3], s[66:67]
	s_mov_b32 s26, s68
	s_waitcnt lgkmcnt(0)
	s_barrier
	s_cmpk_gt_i32 s26, 0xff
	s_cbranch_scc1 .LBB0_817
	s_load_dwordx2 s[4:5], s[2:3], 0x120
	s_nop 0
	s_load_dwordx2 s[2:3], s[2:3], 0xe0
	s_waitcnt lgkmcnt(0)
	s_add_u32 s10, s4, 0x13200000
	s_addc_u32 s11, s5, 0
	s_add_u32 s12, s4, 0x3200000
	s_addc_u32 s13, s5, 0
	s_add_u32 s27, s4, 0x1c600000
	s_addc_u32 s28, s5, 0
	s_add_u32 s14, s4, 0x1b200000
	s_addc_u32 s15, s5, 0
	s_add_u32 s16, s4, 0x30c0000
	s_addc_u32 s17, s5, 0
	s_branch .LBB0_757

.LBB0_817:
	s_setprio 0
	s_mov_b64 s[4:5], s[66:67]
	s_getreg_b32 s6, hwreg(HW_REG_XCC_ID, 0, 4)
	s_waitcnt vmcnt(0)
	s_barrier
	s_mov_b64 s[2:3], exec
	v_readlane_b32 s8, v255, 0
	v_readlane_b32 s9, v255, 1
	s_and_b64 s[8:9], s[2:3], s[8:9]
	s_mov_b64 exec, s[8:9]
	s_cbranch_execz .LBB0_869
	v_readlane_b32 s7, v255, 3
	s_load_dwordx2 s[4:5], s[4:5], 0x120
	s_waitcnt vmcnt(0) expcnt(0) lgkmcnt(0)
	v_mov_b32_e32 v1, s7
	ds_read_b32 v3, v1
	v_readlane_b32 s7, v255, 4
	s_and_b32 s33, s6, 15
	s_waitcnt lgkmcnt(0)
	v_cmp_ne_u32_e32 vcc, 0, v3
	v_mov_b32_e32 v1, s7
	ds_read_b32 v2, v1
	s_cbranch_vccnz .LBB0_833
	s_add_u32 s6, s4, 0x31c0200
	s_addc_u32 s7, s5, 0
	s_add_u32 s8, s4, 0x31c0400
	s_addc_u32 s9, s5, 0
	s_add_u32 s10, s4, 0x31c0500
	s_addc_u32 s11, s5, 0
	s_add_u32 s12, s4, 0x31c0600
	s_addc_u32 s13, s5, 0
	s_add_u32 s14, s4, 0x31c0700
	s_addc_u32 s15, s5, 0
	s_add_u32 s16, s4, 0x31c0800
	s_addc_u32 s17, s5, 0
	s_add_u32 s18, s4, 0x31c0900
	s_addc_u32 s19, s5, 0
	s_add_u32 s20, s4, 0x31c0a00
	s_addc_u32 s21, s5, 0
	s_add_u32 s22, s4, 0x31c0b00
	s_addc_u32 s23, s5, 0
	s_add_u32 s24, s4, 0x31c0c00
	s_addc_u32 s25, s5, 0
	s_add_u32 s26, s4, 0x31c0d00
	s_addc_u32 s27, s5, 0
	s_add_u32 s28, s4, 0x31c0e00
	s_addc_u32 s29, s5, 0
	s_add_u32 s30, s4, 0x31c0f00
	s_addc_u32 s31, s5, 0
	s_add_u32 s34, s4, 0x31c1000
	s_addc_u32 s35, s5, 0
	s_add_u32 s36, s4, 0x31c1100
	s_addc_u32 s37, s5, 0
	s_add_u32 s38, s4, 0x31c1200
	s_addc_u32 s39, s5, 0
	s_add_u32 s40, s4, 0x31c1300
	s_addc_u32 s41, s5, 0
	s_mov_b32 s48, 1
	s_branch .LBB0_821
